# seams 2,3 -> 4-workgroup tile-group barriers (placement-checked), P4a chunk remapped into own tile, TU halo write-through; plus flat release
# speedup vs baseline: 1.0303x; 1.0216x over previous
.LBB0_6:
	s_or_b64 exec, exec, s[4:5]
	s_and_saveexec_b64 s[4:5], s[98:99]
	s_cbranch_execz .Lmy_u_done
	s_and_b32 s6, s90, 7
	s_lshl_b32 s6, s6, 2
	s_lshl_b32 s7, 1, s6
	s_and_b32 s6, s2, 63
	s_lshl_b32 s6, s6, 2
	s_add_i32 s6, s6, 15600
	v_mov_b32_e32 v2, s6
	v_mov_b32_e32 v20, s7
	global_atomic_add v2, v20, s[52:53]

.LBB0_125:
	s_and_b32 s0, s2, 63
	s_lshl_b32 s0, s0, 2
	s_add_i32 s0, s0, 15600
	v_mov_b32_e32 v0, s0
	global_load_dword v0, v0, s[52:53] sc1
	s_and_b32 s0, s90, 7
	s_lshl_b32 s0, s0, 2
	s_waitcnt vmcnt(0)
	v_readfirstlane_b32 s1, v0
	s_lshr_b32 s1, s1, s0
	s_and_b32 s1, s1, 15
	s_cmp_eq_u32 s1, 4
	s_cselect_b32 s1, 1, 0
	v_writelane_b32 v242, s1, 13
	s_add_u32 s48, s52, 0x2000000
	s_addc_u32 s49, s53, 0
	s_add_u32 s28, s52, 0x8000000
	s_addc_u32 s29, s53, 0
	s_add_u32 s18, s52, 0x1a00000
	s_addc_u32 s19, s53, 0
	s_add_u32 s36, s52, 0x1b00000
	s_addc_u32 s37, s53, 0
	s_add_u32 s20, s52, 0x1c00000
	s_addc_u32 s21, s53, 0
	v_mov_b32_e32 v10, v196
	s_cmpk_lt_i32 s2, 0x400
	s_cselect_b64 s[88:89], -1, 0
	s_cmpk_gt_i32 s2, 0x3ff
	v_readfirstlane_b32 s5, v10
	s_cbranch_scc1 .LBB0_161
	s_ashr_i32 s3, s2, 31
	s_lshr_b32 s0, s3, 29
	s_add_i32 s6, s2, s0
	s_and_b32 s0, s6, -8
	s_sub_i32 s7, s2, s0
	s_cmp_gt_i32 s7, -1
	s_cbranch_scc0 .LBB0_128
	s_lshl_b32 s4, s7, 7
	s_mov_b64 s[0:1], 0
	s_branch .LBB0_129

.LBB0_146:
	v_lshl_or_b32 v170, s83, 6, v176
	v_ashrrev_i32_e32 v171, 31, v170
	v_lshlrev_b64 v[172:173], 2, v[170:171]
	v_lshl_add_u64 v[96:97], s[42:43], 0, v[172:173]
	v_lshl_add_u64 v[100:101], s[70:71], 0, v[172:173]
	v_lshl_add_u64 v[112:113], s[72:73], 0, v[172:173]
	global_load_dwordx4 v[96:99], v[96:97], off
	s_nop 0
	global_load_dwordx4 v[100:103], v[100:101], off
	v_cndmask_b32_e64 v122, 0, 1, s[60:61]
	global_load_dwordx4 v[112:115], v[112:113], off
	v_pk_mul_f32 v[144:145], v[72:73], v[64:65]
	v_pk_mul_f32 v[120:121], v[8:9], v[4:5]
	v_cmp_ne_u32_e64 s[0:1], 1, v122
	s_and_saveexec_b64 s[84:85], s[4:5]
	s_cbranch_execz .LBB0_149
	v_pk_mul_f32 v[146:147], v[74:75], v[66:67]
	v_pk_mul_f32 v[122:123], v[10:11], v[6:7]
	s_and_b64 vcc, exec, s[0:1]
	ds_write_b128 v177, v[144:147]
	ds_write_b128 v178, v[120:123]
	s_cbranch_vccnz .LBB0_149
	s_ashr_i32 s83, s82, 31
	s_lshl_b64 s[14:15], s[82:83], 13
	v_lshl_add_u64 v[4:5], v[156:157], 0, s[14:15]
	v_lshl_add_u64 v[4:5], v[170:171], 2, v[4:5]
	global_store_dwordx4 v[4:5], v[120:123], off sc1

.LBB0_161:
	v_cndmask_b32_e64 v0, 0, 1, s[46:47]
	v_cmp_ne_u32_e64 s[4:5], 1, v0
	s_waitcnt vmcnt(0) lgkmcnt(0)
	s_barrier
	s_and_saveexec_b64 s[0:1], s[98:99]
	s_cbranch_execz .Lmy_s2_done
	v_readlane_b32 s8, v242, 13
	s_cmp_eq_u32 s8, 1
	s_cbranch_scc1 .Lmy_s2_uni
	buffer_wbl2 sc1
	s_waitcnt vmcnt(0)
.Lmy_s2_uni:
	s_and_b32 s8, s2, 63
	s_lshl_b32 s9, s8, 2
	s_add_i32 s9, s9, 14800
	v_mov_b32_e32 v0, s9
	v_mov_b32_e32 v1, 1
	global_atomic_add v0, v1, s[52:53]
	s_and_b32 s11, s8, 7
	s_lshr_b32 s14, s8, 3
	s_lshl_b32 s15, s11, 3
	s_add_i32 s15, s15, s14
	s_sub_i32 s15, s15, 1
	s_max_i32 s15, s15, 0
	s_lshr_b32 s11, s15, 3
	s_and_b32 s14, s15, 7
	s_lshl_b32 s14, s14, 3
	s_add_i32 s11, s11, s14
	s_lshl_b32 s11, s11, 2
	s_add_i32 s11, s11, 14800
	v_mov_b32_e32 v2, s11
	s_mov_b32 s14, 0
.Lmy_s2_poll:
	global_load_dword v1, v0, s[52:53] sc1
	global_load_dword v3, v2, s[52:53] sc1
	s_waitcnt vmcnt(0)
	v_min_u32_e32 v1, v1, v3
	v_cmp_gt_u32_e32 vcc, 4, v1
	s_cbranch_vccz .Lmy_s2_ready
	s_sleep 1
	s_add_u32 s14, s14, 1
	s_cmp_lt_u32 s14, 0x8000
	s_cbranch_scc1 .Lmy_s2_poll
.Lmy_s2_ready:
	buffer_inv sc1
	s_waitcnt vmcnt(0)
.Lmy_s2_done:
	s_or_b64 exec, exec, s[0:1]
	s_barrier
	s_branch .LBB0_227
	v_or_b32_e32 v0, v203, v202
	s_movk_i32 s0, 0x3ff
	v_and_or_b32 v0, v0, s0, v196
	v_cmp_eq_u32_e32 vcc, 0, v0
	s_waitcnt lgkmcnt(0)
	s_barrier
	s_and_saveexec_b64 s[0:1], vcc
	s_cbranch_execz .LBB0_172
	v_readlane_b32 s6, v242, 0
	v_readlane_b32 s7, v242, 1
	buffer_wbl2 sc1
	s_waitcnt vmcnt(0)
	s_load_dwordx2 s[6:7], s[6:7], 0x58
	v_mov_b32_e32 v2, 0
	s_mov_b64 s[8:9], exec
	v_mbcnt_lo_u32_b32 v1, s8, 0
	v_mbcnt_hi_u32_b32 v1, s9, v1
	s_waitcnt lgkmcnt(0)
	global_load_dword v0, v2, s[6:7] offset:40
	v_cmp_eq_u32_e32 vcc, 0, v1
	s_and_saveexec_b64 s[10:11], vcc
	s_cbranch_execz .LBB0_165
	s_bcnt1_i32_b64 s3, s[8:9]
	v_mov_b32_e32 v3, s3
	global_atomic_add v3, v2, v3, s[6:7] offset:32 sc0

.LBB0_282:
	s_waitcnt vmcnt(0) lgkmcnt(0)
	s_barrier
	s_and_saveexec_b64 s[0:1], s[98:99]
	s_cbranch_execz .Lmy_s3_done
	v_readlane_b32 s8, v242, 13
	s_cmp_eq_u32 s8, 1
	s_cbranch_scc1 .Lmy_s3_uni
	buffer_wbl2 sc1
	s_waitcnt vmcnt(0)
.Lmy_s3_uni:
	s_and_b32 s8, s2, 63
	s_lshl_b32 s9, s8, 2
	s_add_i32 s9, s9, 15200
	v_mov_b32_e32 v0, s9
	v_mov_b32_e32 v1, 1
	global_atomic_add v0, v1, s[52:53]
	v_mov_b32_e32 v2, s9
	s_mov_b32 s14, 0

.Lmy_s3_done:
	s_or_b64 exec, exec, s[0:1]
	s_barrier
	s_branch .LBB0_348
	v_or_b32_e32 v0, v203, v202
	s_movk_i32 s0, 0x3ff
	v_and_or_b32 v0, v0, s0, v196
	v_cmp_eq_u32_e32 vcc, 0, v0
	s_waitcnt lgkmcnt(0)
	s_barrier
	s_and_saveexec_b64 s[0:1], vcc
	s_cbranch_execz .LBB0_293
	v_readlane_b32 s8, v242, 0
	v_readlane_b32 s9, v242, 1
	buffer_wbl2 sc1
	s_waitcnt vmcnt(0)
	s_load_dwordx2 s[8:9], s[8:9], 0x58
	v_mov_b32_e32 v2, 0
	s_mov_b64 s[10:11], exec
	v_mbcnt_lo_u32_b32 v1, s10, 0
	v_mbcnt_hi_u32_b32 v1, s11, v1
	s_waitcnt lgkmcnt(0)
	global_load_dword v0, v2, s[8:9] offset:40
	v_cmp_eq_u32_e32 vcc, 0, v1
	s_and_saveexec_b64 s[12:13], vcc
	s_cbranch_execz .LBB0_286
	s_bcnt1_i32_b64 s10, s[10:11]
	v_mov_b32_e32 v3, s10
	global_atomic_add v3, v2, v3, s[8:9] offset:32 sc0

.LBB0_348:
	s_add_u32 s38, s52, 0x1800000
	s_addc_u32 s39, s53, 0
	s_add_u32 s74, s52, 0x1900000
	s_addc_u32 s75, s53, 0
	s_bitcmp0_b32 s2, 0
	s_cselect_b64 s[62:63], -1, 0
	s_and_b64 s[0:1], s[62:63], s[42:43]
	s_mov_b32 s23, 0
	s_andn2_b64 vcc, exec, s[0:1]
	v_and_b32_e32 v171, 15, v196
	v_lshrrev_b32_e32 v197, 4, v204
	v_cmp_eq_u32_e64 s[0:1], 63, v204
	s_waitcnt lgkmcnt(0)
	s_cbranch_vccnz .LBB0_355
	v_lshlrev_b32_e32 v0, 3, v197
	v_readlane_b32 s14, v242, 2
	v_mov_b32_e32 v1, 0
	v_mbcnt_hi_u32_b32 v9, -1, v205
	v_lshl_or_b32 v7, s14, 7, v0
	v_lshlrev_b32_e32 v0, 11, v171
	v_lshl_add_u64 v[2:3], s[40:41], 0, v[0:1]
	v_lshlrev_b32_e32 v0, 1, v7
	v_and_b32_e32 v11, 64, v9
	v_lshl_add_u64 v[2:3], v[2:3], 0, v[0:1]
	v_lshl_add_u64 v[4:5], s[36:37], 0, v[0:1]
	v_or_b32_e32 v0, 32, v7
	v_or_b32_e32 v6, 64, v7
	v_or_b32_e32 v8, 0x60, v7
	v_add_u32_e32 v7, -1, v9
	v_cmp_lt_i32_e32 vcc, v7, v11
	s_and_b32 s8, s97, 0x3ffffc0
	s_lshl_b32 s8, s8, 6
	v_cndmask_b32_e32 v7, v7, v9, vcc
	v_lshlrev_b32_e32 v13, 2, v7
	v_add_u32_e32 v7, -2, v9
	v_cmp_lt_i32_e32 vcc, v7, v11
	v_lshl_or_b32 v19, v197, 8, s8
	s_lshl_b32 s8, s14, 3
	v_cndmask_b32_e32 v7, v7, v9, vcc
	v_lshlrev_b32_e32 v14, 2, v7
	v_add_u32_e32 v7, -4, v9
	v_cmp_lt_i32_e32 vcc, v7, v11
	s_lshl_b32 s22, s14, 1
	s_add_i32 s9, s8, 0
	v_cndmask_b32_e32 v7, v7, v9, vcc
	v_lshlrev_b32_e32 v15, 2, v7
	v_add_u32_e32 v7, -8, v9
	v_cmp_lt_i32_e32 vcc, v7, v11
	v_lshl_add_u32 v10, v171, 2, 0
	s_add_u32 s42, s50, s8
	v_cndmask_b32_e32 v7, v7, v9, vcc
	v_lshlrev_b32_e32 v16, 2, v7
	v_add_u32_e32 v7, -16, v9
	v_cmp_lt_i32_e32 vcc, v7, v11
	s_addc_u32 s43, s51, 0
	s_lshl_b64 s[46:47], s[22:23], 16
	v_cndmask_b32_e32 v7, v7, v9, vcc
	v_lshlrev_b32_e32 v17, 2, v7
	v_subrev_u32_e32 v7, 32, v9
	v_cmp_lt_i32_e32 vcc, v7, v11
	s_or_b32 s22, s22, 1
	v_add_u32_e32 v19, v10, v19
	v_cndmask_b32_e32 v7, v7, v9, vcc
	v_lshl_add_u32 v12, v204, 6, s9
	v_cmp_eq_u32_e64 s[8:9], 0, v204
	v_cmp_gt_u32_e64 s[10:11], 2, v204
	v_cmp_gt_u32_e64 s[12:13], 4, v204
	v_cmp_gt_u32_e64 s[16:17], 8, v204
	v_cmp_gt_u32_e64 s[18:19], 16, v204
	v_lshlrev_b32_e32 v18, 2, v7
	v_cmp_gt_u32_e64 s[20:21], 32, v204
	s_lshl_b32 s14, s14, 9
	s_lshl_b64 s[48:49], s[22:23], 16
	s_lshl_b32 s56, s54, 6
	v_lshlrev_b32_e32 v0, 1, v0
	v_lshlrev_b32_e32 v6, 1, v6
	v_mov_b32_e32 v7, v1
	v_lshlrev_b32_e32 v8, 1, v8
	v_mov_b32_e32 v9, v1
	v_mov_b32_e32 v20, 0x358637bd
	s_mov_b32 s57, 0xf800000
	v_mov_b32_e32 v21, 0x260
	s_mov_b32 s64, 0xbfb8aa3b
	v_add_u32_e32 v22, 0x400, v19
	v_add_u32_e32 v23, 0x800, v19
	v_add_u32_e32 v24, 0xc00, v19
	s_and_b32 s65, s2, 7
	s_lshl_b32 s65, s65, 3
	s_bfe_u32 s15, s2, 0x30003
	s_add_i32 s65, s65, s15
	s_lshl_b32 s65, s65, 2
	s_lshr_b32 s15, s2, 6
	s_add_i32 s65, s65, s15
	s_lshl_b32 s15, s65, 6
	s_branch .LBB0_351

.LBB0_440:
	s_cmpk_lt_i32 s2, 0x100
	s_cselect_b64 s[0:1], -1, 0
	s_xor_b64 s[8:9], s[62:63], -1
	s_and_b64 s[0:1], s[0:1], s[8:9]
	s_and_b64 vcc, exec, s[0:1]
	s_cbranch_vccz .LBB0_447
	v_lshlrev_b32_e32 v0, 3, v197
	v_readlane_b32 s14, v242, 2
	v_mov_b32_e32 v1, 0
	v_mbcnt_hi_u32_b32 v9, -1, v205
	v_lshl_or_b32 v7, s14, 7, v0
	v_lshlrev_b32_e32 v0, 11, v171
	v_lshl_add_u64 v[2:3], s[40:41], 0, v[0:1]
	v_lshlrev_b32_e32 v0, 1, v7
	v_and_b32_e32 v11, 64, v9
	v_lshl_add_u64 v[2:3], v[2:3], 0, v[0:1]
	v_lshl_add_u64 v[4:5], s[36:37], 0, v[0:1]
	v_or_b32_e32 v0, 32, v7
	v_or_b32_e32 v6, 64, v7
	v_or_b32_e32 v8, 0x60, v7
	v_add_u32_e32 v7, -1, v9
	v_cmp_lt_i32_e32 vcc, v7, v11
	s_and_b32 s8, s97, 0x3ffffc0
	s_lshl_b32 s8, s8, 6
	v_cndmask_b32_e32 v7, v7, v9, vcc
	v_lshlrev_b32_e32 v13, 2, v7
	v_add_u32_e32 v7, -2, v9
	v_cmp_lt_i32_e32 vcc, v7, v11
	v_lshl_or_b32 v19, v197, 8, s8
	s_lshl_b32 s8, s14, 3
	v_cndmask_b32_e32 v7, v7, v9, vcc
	v_lshlrev_b32_e32 v14, 2, v7
	v_add_u32_e32 v7, -4, v9
	v_cmp_lt_i32_e32 vcc, v7, v11
	s_lshl_b32 s22, s14, 1
	s_add_i32 s9, s8, 0
	v_cndmask_b32_e32 v7, v7, v9, vcc
	v_lshlrev_b32_e32 v15, 2, v7
	v_add_u32_e32 v7, -8, v9
	v_cmp_lt_i32_e32 vcc, v7, v11
	s_mov_b32 s23, 0
	v_lshl_add_u32 v10, v171, 2, 0
	v_cndmask_b32_e32 v7, v7, v9, vcc
	v_lshlrev_b32_e32 v16, 2, v7
	v_add_u32_e32 v7, -16, v9
	v_cmp_lt_i32_e32 vcc, v7, v11
	s_add_u32 s40, s50, s8
	s_addc_u32 s41, s51, 0
	v_cndmask_b32_e32 v7, v7, v9, vcc
	v_lshlrev_b32_e32 v17, 2, v7
	v_subrev_u32_e32 v7, 32, v9
	v_cmp_lt_i32_e32 vcc, v7, v11
	s_lshl_b64 s[58:59], s[22:23], 16
	s_or_b32 s22, s22, 1
	v_cndmask_b32_e32 v7, v7, v9, vcc
	v_add_u32_e32 v19, v10, v19
	v_cmp_eq_u32_e64 s[0:1], 63, v204
	v_lshl_add_u32 v12, v204, 6, s9
	v_cmp_eq_u32_e64 s[8:9], 0, v204
	v_cmp_gt_u32_e64 s[10:11], 2, v204
	v_cmp_gt_u32_e64 s[12:13], 4, v204
	v_cmp_gt_u32_e64 s[16:17], 8, v204
	v_cmp_gt_u32_e64 s[18:19], 16, v204
	v_lshlrev_b32_e32 v18, 2, v7
	v_cmp_gt_u32_e64 s[20:21], 32, v204
	s_lshl_b32 s14, s14, 9
	s_lshl_b64 s[62:63], s[22:23], 16
	s_lshl_b32 s56, s54, 6
	v_lshlrev_b32_e32 v0, 1, v0
	v_lshlrev_b32_e32 v6, 1, v6
	v_mov_b32_e32 v7, v1
	v_lshlrev_b32_e32 v8, 1, v8
	v_mov_b32_e32 v9, v1
	v_mov_b32_e32 v20, 0x358637bd
	s_mov_b32 s57, 0xf800000
	v_mov_b32_e32 v21, 0x260
	s_mov_b32 s64, 0xbfb8aa3b
	v_add_u32_e32 v22, 0x400, v19
	v_add_u32_e32 v23, 0x800, v19
	v_add_u32_e32 v24, 0xc00, v19
	s_and_b32 s65, s2, 7
	s_lshl_b32 s65, s65, 3
	s_bfe_u32 s15, s2, 0x30003
	s_add_i32 s65, s65, s15
	s_lshl_b32 s65, s65, 2
	s_lshr_b32 s15, s2, 6
	s_add_i32 s65, s65, s15
	s_lshl_b32 s15, s65, 6
	s_branch .LBB0_443
